# P0: COMB absorption items moved to even waves after XN+rotary; QABS loop batched 16 d per round trip
# speedup vs baseline: 1.0226x; 1.0015x over previous
.LBB0_9:
	s_load_dwordx16 s[8:23], s[0:1], 0x0
	s_cmpk_lt_i32 s28, 0x3e9
	s_waitcnt lgkmcnt(0)
	v_writelane_b32 v244, s8, 0
	s_nop 1
	v_writelane_b32 v244, s9, 1
	v_writelane_b32 v244, s10, 2
	v_writelane_b32 v244, s11, 3
	v_writelane_b32 v244, s12, 4
	v_writelane_b32 v244, s13, 5
	v_writelane_b32 v244, s14, 6
	v_writelane_b32 v244, s15, 7
	v_writelane_b32 v244, s16, 8
	v_writelane_b32 v244, s17, 9
	v_writelane_b32 v244, s18, 10
	v_writelane_b32 v244, s19, 11
	v_writelane_b32 v244, s20, 12
	v_writelane_b32 v244, s21, 13
	v_writelane_b32 v244, s22, 14
	v_writelane_b32 v244, s23, 15
	v_writelane_b32 v244, s0, 62
	v_writelane_b32 v244, s1, 63
	s_cbranch_scc1 .LBB0_21
	v_lshrrev_b32_e32 v1, 20, v0
	v_lshrrev_b32_e32 v0, 10, v0
	v_or_b32_e32 v0, v0, v1
	s_movk_i32 s6, 0x3ff
	v_and_or_b32 v0, v0, s6, v209
	v_cmp_eq_u32_e32 vcc, 0, v0
	s_barrier
	s_and_saveexec_b64 s[6:7], vcc
	s_cbranch_execz .LBB0_20
	buffer_wbl2 sc1
	s_waitcnt vmcnt(0)
	s_load_dwordx2 s[4:5], s[4:5], 0x58
	v_mov_b32_e32 v2, 0
	s_mov_b64 s[8:9], exec
	v_mbcnt_lo_u32_b32 v1, s8, 0
	v_mbcnt_hi_u32_b32 v1, s9, v1
	s_waitcnt lgkmcnt(0)
	global_load_dword v0, v2, s[4:5] offset:40
	v_cmp_eq_u32_e32 vcc, 0, v1
	s_and_saveexec_b64 s[10:11], vcc
	s_cbranch_execz .LBB0_13
	s_bcnt1_i32_b64 s8, s[8:9]
	v_mov_b32_e32 v3, s8
	global_atomic_add v3, v2, v3, s[4:5] offset:32 sc0

.Leven_items:
	v_readlane_b32 s4, v244, 17
	s_ashr_i32 s34, s4, 1
	s_cmpk_lt_i32 s34, 0x2640
	v_readlane_b32 s5, v244, 18
	s_cbranch_scc1 .LBB0_25
	s_lshl_b32 s70, s34, 6
	s_cbranch_execz .LBB0_26
	s_branch .LBB0_127

.LBB0_29:
	v_readfirstlane_b32 s0, v209
	s_cmpk_gt_i32 s34, 0x223f
	s_cselect_b32 s1, 64, 0
	s_and_b32 s0, s0, 64
	s_xor_b32 s0, s0, s1
	s_cmp_eq_u32 s0, 0
	s_cbranch_scc1 .LBB0_28
	s_cmpk_gt_i32 s34, 0x5ff
	s_mov_b64 s[0:1], -1
	s_cbranch_scc0 .LBB0_101
	s_cmpk_gt_u32 s34, 0x63f
	s_cbranch_scc0 .LBB0_80
	s_cmpk_gt_u32 s34, 0x83f
	s_cbranch_scc0 .LBB0_75
	s_lshl_b32 s0, s65, 2
	s_and_b32 s0, s0, 0xf00
	v_lshl_or_b32 v0, v203, 2, s0
	v_mov_b32_e32 v1, v45
	s_cmpk_gt_u32 s34, 0x103f
	s_mov_b64 s[0:1], -1
	s_cbranch_scc0 .LBB0_70
	s_cmpk_gt_u32 s34, 0x123f
	s_cbranch_scc0 .LBB0_65
	s_cmpk_gt_u32 s34, 0x1a3f
	s_cbranch_scc0 .LBB0_44
	s_cmpk_gt_u32 s34, 0x223f
	s_cbranch_scc0 .LBB0_39
	s_lshr_b32 s4, s80, 8
	v_readlane_b32 s12, v244, 0
	s_lshl_b64 s[0:1], s[4:5], 19
	v_readlane_b32 s26, v244, 14
	v_readlane_b32 s27, v244, 15
	s_add_u32 s0, s26, s0
	s_addc_u32 s1, s27, s1
	v_readlane_b32 s24, v244, 12
	v_lshl_add_u64 v[2:3], s[0:1], 0, v[0:1]
	s_lshl_b64 s[0:1], s[4:5], 9
	v_readlane_b32 s25, v244, 13
	s_add_u32 s4, s24, s0
	s_addc_u32 s10, s25, s1
	s_lshl_b64 s[0:1], s[80:81], 8
	v_readlane_b32 s22, v244, 10
	s_and_b32 s1, s1, 0xff
	s_and_b32 s0, s0, 0xfffff000
	v_readlane_b32 s23, v244, 11
	s_add_u32 s11, s22, s0
	v_mov_b32_e32 v4, 0
	s_addc_u32 s88, s23, s1
	s_mov_b64 s[0:1], 0
	v_mov_b32_e32 v5, v4
	v_mov_b32_e32 v6, v4
	v_mov_b32_e32 v8, v4
	v_mov_b32_e32 v7, v4
	v_mov_b32_e32 v9, v4
	v_mov_b32_e32 v10, v4
	v_mov_b32_e32 v11, v4
	v_readlane_b32 s13, v244, 1
	v_readlane_b32 s14, v244, 2
	v_readlane_b32 s15, v244, 3
	v_readlane_b32 s16, v244, 4
	v_readlane_b32 s17, v244, 5
	v_readlane_b32 s18, v244, 6
	v_readlane_b32 s19, v244, 7
	v_readlane_b32 s20, v244, 8
	v_readlane_b32 s21, v244, 9
	s_mov_b64 s[14:15], 0x2000
	s_mov_b64 s[16:17], 0x3000

.LBB0_75:
	s_andn2_b64 vcc, exec, s[0:1]
	s_cbranch_vccnz .LBB0_79
	v_lshlrev_b32_e32 v0, 8, v87
	v_and_b32_e32 v44, 0xfe000, v0
	v_lshrrev_b32_e32 v0, 2, v87
	v_and_b32_e32 v0, 0x3ffffc00, v0
	v_mov_b32_e32 v1, v45
	v_lshl_add_u64 v[0:1], v[44:45], 0, v[0:1]
	v_lshl_add_u32 v103, s34, 6, v55
	v_lshl_add_u64 v[66:67], s[28:29], 0, v[0:1]
	v_lshrrev_b32_e32 v2, 12, v103
	v_lshlrev_b32_e32 v0, 3, v103
	v_and_b32_e32 v57, 0xf8, v0
	v_mov_b64_e32 v[0:1], s[38:39]
	v_mul_u32_u24_e32 v2, 0xc0, v2
	v_mad_u64_u32 v[0:1], s[0:1], v57, s30, v[0:1]
	v_lshlrev_b32_e32 v44, 2, v2
	v_mov_b32_e32 v58, 0
	v_lshl_add_u64 v[68:69], v[0:1], 0, v[44:45]
	s_mov_b64 s[0:1], 0
	v_mov_b32_e32 v59, v58
	v_mov_b32_e32 v62, v58
	v_mov_b32_e32 v60, v58
	v_mov_b32_e32 v63, v58
	v_mov_b32_e32 v61, v58
	v_mov_b32_e32 v64, v58
	v_mov_b32_e32 v65, v58
	s_mov_b64 s[12:13], 0x1800
.Lqabs_loop:
	v_lshl_add_u64 v[204:205], v[66:67], 0, s[0:1]
	global_load_dwordx4 v[0:3], v[204:205], off offset:-16
	global_load_dwordx4 v[4:7], v[204:205], off
	global_load_dwordx4 v[8:11], v[204:205], off offset:16
	global_load_dwordx4 v[12:15], v[204:205], off offset:32
	v_lshl_add_u64 v[206:207], v[68:69], 0, s[0:1]
	global_load_dwordx4 v[16:19], v[206:207], off
	global_load_dwordx4 v[20:23], v[206:207], off offset:16
	global_load_dwordx4 v[24:27], v[206:207], off offset:32
	global_load_dwordx4 v[28:31], v[206:207], off offset:48
	v_lshl_add_u64 v[206:207], v[206:207], 0, s[12:13]
	global_load_dwordx4 v[32:35], v[206:207], off
	global_load_dwordx4 v[36:39], v[206:207], off offset:16
	global_load_dwordx4 v[104:107], v[206:207], off offset:32
	global_load_dwordx4 v[108:111], v[206:207], off offset:48
	v_lshl_add_u64 v[206:207], v[206:207], 0, s[12:13]
	global_load_dwordx4 v[112:115], v[206:207], off
	global_load_dwordx4 v[116:119], v[206:207], off offset:16
	global_load_dwordx4 v[120:123], v[206:207], off offset:32
	global_load_dwordx4 v[124:127], v[206:207], off offset:48
	v_lshl_add_u64 v[206:207], v[206:207], 0, s[12:13]
	global_load_dwordx4 v[128:131], v[206:207], off
	global_load_dwordx4 v[132:135], v[206:207], off offset:16
	global_load_dwordx4 v[138:141], v[206:207], off offset:32
	global_load_dwordx4 v[142:145], v[206:207], off offset:48
	v_lshl_add_u64 v[206:207], v[206:207], 0, s[12:13]
	global_load_dwordx4 v[146:149], v[206:207], off
	global_load_dwordx4 v[150:153], v[206:207], off offset:16
	global_load_dwordx4 v[154:157], v[206:207], off offset:32
	global_load_dwordx4 v[158:161], v[206:207], off offset:48
	v_lshl_add_u64 v[206:207], v[206:207], 0, s[12:13]
	global_load_dwordx4 v[162:165], v[206:207], off
	global_load_dwordx4 v[166:169], v[206:207], off offset:16
	global_load_dwordx4 v[170:173], v[206:207], off offset:32
	global_load_dwordx4 v[174:177], v[206:207], off offset:48
	v_lshl_add_u64 v[206:207], v[206:207], 0, s[12:13]
	global_load_dwordx4 v[178:181], v[206:207], off
	global_load_dwordx4 v[182:185], v[206:207], off offset:16
	global_load_dwordx4 v[186:189], v[206:207], off offset:32
	global_load_dwordx4 v[190:193], v[206:207], off offset:48
	v_lshl_add_u64 v[206:207], v[206:207], 0, s[12:13]
	global_load_dwordx4 v[194:197], v[206:207], off
	global_load_dwordx4 v[198:201], v[206:207], off offset:16
	global_load_dwordx4 v[210:213], v[206:207], off offset:32
	global_load_dwordx4 v[214:217], v[206:207], off offset:48
	s_add_u32 s0, s0, 64
	s_addc_u32 s1, s1, 0
	s_waitcnt vmcnt(0)
	v_fmac_f32_e32 v62, v0, v16
	v_fmac_f32_e32 v60, v0, v32
	v_fmac_f32_e32 v63, v0, v112
	v_fmac_f32_e32 v61, v0, v128
	v_fmac_f32_e32 v58, v0, v146
	v_fmac_f32_e32 v64, v0, v162
	v_fmac_f32_e32 v59, v0, v178
	v_fmac_f32_e32 v65, v0, v194
	v_fmac_f32_e32 v62, v1, v17
	v_fmac_f32_e32 v60, v1, v33
	v_fmac_f32_e32 v63, v1, v113
	v_fmac_f32_e32 v61, v1, v129
	v_fmac_f32_e32 v58, v1, v147
	v_fmac_f32_e32 v64, v1, v163
	v_fmac_f32_e32 v59, v1, v179
	v_fmac_f32_e32 v65, v1, v195
	v_fmac_f32_e32 v62, v2, v18
	v_fmac_f32_e32 v60, v2, v34
	v_fmac_f32_e32 v63, v2, v114
	v_fmac_f32_e32 v61, v2, v130
	v_fmac_f32_e32 v58, v2, v148
	v_fmac_f32_e32 v64, v2, v164
	v_fmac_f32_e32 v59, v2, v180
	v_fmac_f32_e32 v65, v2, v196
	v_fmac_f32_e32 v62, v3, v19
	v_fmac_f32_e32 v60, v3, v35
	v_fmac_f32_e32 v63, v3, v115
	v_fmac_f32_e32 v61, v3, v131
	v_fmac_f32_e32 v58, v3, v149
	v_fmac_f32_e32 v64, v3, v165
	v_fmac_f32_e32 v59, v3, v181
	v_fmac_f32_e32 v65, v3, v197
	v_fmac_f32_e32 v62, v4, v20
	v_fmac_f32_e32 v60, v4, v36
	v_fmac_f32_e32 v63, v4, v116
	v_fmac_f32_e32 v61, v4, v132
	v_fmac_f32_e32 v58, v4, v150
	v_fmac_f32_e32 v64, v4, v166
	v_fmac_f32_e32 v59, v4, v182
	v_fmac_f32_e32 v65, v4, v198
	v_fmac_f32_e32 v62, v5, v21
	v_fmac_f32_e32 v60, v5, v37
	v_fmac_f32_e32 v63, v5, v117
	v_fmac_f32_e32 v61, v5, v133
	v_fmac_f32_e32 v58, v5, v151
	v_fmac_f32_e32 v64, v5, v167
	v_fmac_f32_e32 v59, v5, v183
	v_fmac_f32_e32 v65, v5, v199
	v_fmac_f32_e32 v62, v6, v22
	v_fmac_f32_e32 v60, v6, v38
	v_fmac_f32_e32 v63, v6, v118
	v_fmac_f32_e32 v61, v6, v134
	v_fmac_f32_e32 v58, v6, v152
	v_fmac_f32_e32 v64, v6, v168
	v_fmac_f32_e32 v59, v6, v184
	v_fmac_f32_e32 v65, v6, v200
	v_fmac_f32_e32 v62, v7, v23
	v_fmac_f32_e32 v60, v7, v39
	v_fmac_f32_e32 v63, v7, v119
	v_fmac_f32_e32 v61, v7, v135
	v_fmac_f32_e32 v58, v7, v153
	v_fmac_f32_e32 v64, v7, v169
	v_fmac_f32_e32 v59, v7, v185
	v_fmac_f32_e32 v65, v7, v201
	v_fmac_f32_e32 v62, v8, v24
	v_fmac_f32_e32 v60, v8, v104
	v_fmac_f32_e32 v63, v8, v120
	v_fmac_f32_e32 v61, v8, v138
	v_fmac_f32_e32 v58, v8, v154
	v_fmac_f32_e32 v64, v8, v170
	v_fmac_f32_e32 v59, v8, v186
	v_fmac_f32_e32 v65, v8, v210
	v_fmac_f32_e32 v62, v9, v25
	v_fmac_f32_e32 v60, v9, v105
	v_fmac_f32_e32 v63, v9, v121
	v_fmac_f32_e32 v61, v9, v139
	v_fmac_f32_e32 v58, v9, v155
	v_fmac_f32_e32 v64, v9, v171
	v_fmac_f32_e32 v59, v9, v187
	v_fmac_f32_e32 v65, v9, v211
	v_fmac_f32_e32 v62, v10, v26
	v_fmac_f32_e32 v60, v10, v106
	v_fmac_f32_e32 v63, v10, v122
	v_fmac_f32_e32 v61, v10, v140
	v_fmac_f32_e32 v58, v10, v156
	v_fmac_f32_e32 v64, v10, v172
	v_fmac_f32_e32 v59, v10, v188
	v_fmac_f32_e32 v65, v10, v212
	v_fmac_f32_e32 v62, v11, v27
	v_fmac_f32_e32 v60, v11, v107
	v_fmac_f32_e32 v63, v11, v123
	v_fmac_f32_e32 v61, v11, v141
	v_fmac_f32_e32 v58, v11, v157
	v_fmac_f32_e32 v64, v11, v173
	v_fmac_f32_e32 v59, v11, v189
	v_fmac_f32_e32 v65, v11, v213
	v_fmac_f32_e32 v62, v12, v28
	v_fmac_f32_e32 v60, v12, v108
	v_fmac_f32_e32 v63, v12, v124
	v_fmac_f32_e32 v61, v12, v142
	v_fmac_f32_e32 v58, v12, v158
	v_fmac_f32_e32 v64, v12, v174
	v_fmac_f32_e32 v59, v12, v190
	v_fmac_f32_e32 v65, v12, v214
	v_fmac_f32_e32 v62, v13, v29
	v_fmac_f32_e32 v60, v13, v109
	v_fmac_f32_e32 v63, v13, v125
	v_fmac_f32_e32 v61, v13, v143
	v_fmac_f32_e32 v58, v13, v159
	v_fmac_f32_e32 v64, v13, v175
	v_fmac_f32_e32 v59, v13, v191
	v_fmac_f32_e32 v65, v13, v215
	v_fmac_f32_e32 v62, v14, v30
	v_fmac_f32_e32 v60, v14, v110
	v_fmac_f32_e32 v63, v14, v126
	v_fmac_f32_e32 v61, v14, v144
	v_fmac_f32_e32 v58, v14, v160
	v_fmac_f32_e32 v64, v14, v176
	v_fmac_f32_e32 v59, v14, v192
	v_fmac_f32_e32 v65, v14, v216
	v_fmac_f32_e32 v62, v15, v31
	v_fmac_f32_e32 v60, v15, v111
	v_fmac_f32_e32 v63, v15, v127
	v_fmac_f32_e32 v61, v15, v145
	v_fmac_f32_e32 v58, v15, v161
	v_fmac_f32_e32 v64, v15, v177
	v_fmac_f32_e32 v59, v15, v193
	v_fmac_f32_e32 v65, v15, v217
	s_cmpk_eq_i32 s0, 0x200
	s_cbranch_scc0 .Lqabs_loop
	v_lshrrev_b32_e32 v8, 3, v103
	v_lshlrev_b32_e32 v4, 2, v57
	v_and_b32_e32 v8, 0x1fc, v8
	global_load_dwordx4 v[0:3], v4, s[36:37]
	s_nop 0
	global_load_dwordx4 v[4:7], v4, s[36:37] offset:16
	v_lshrrev_b32_e32 v44, 5, v103
	global_load_dword v8, v8, s[40:41]
	v_lshlrev_b64 v[10:11], 9, v[44:45]
	v_lshlrev_b32_e32 v44, 1, v57
	v_lshl_add_u64 v[10:11], s[74:75], 0, v[10:11]
	s_waitcnt vmcnt(2)
	v_mov_b32_e32 v12, v0
	v_mov_b32_e32 v13, v2
	v_mov_b32_e32 v2, v1
	s_waitcnt vmcnt(1)
	v_mov_b32_e32 v0, v4
	v_mov_b32_e32 v1, v6
	v_mov_b32_e32 v6, v5
	s_waitcnt vmcnt(0)
	v_pk_mul_f32 v[4:5], v[62:63], v[8:9] op_sel_hi:[1,0]
	v_pk_mul_f32 v[16:17], v[58:59], v[8:9] op_sel_hi:[1,0]
	v_pk_mul_f32 v[14:15], v[60:61], v[8:9] op_sel_hi:[1,0]
	v_pk_mul_f32 v[8:9], v[64:65], v[8:9] op_sel_hi:[1,0]
	v_pk_mul_f32 v[4:5], v[4:5], v[12:13]
	v_pk_mul_f32 v[0:1], v[16:17], v[0:1]
	v_pk_mul_f32 v[2:3], v[14:15], v[2:3]
	v_pk_mul_f32 v[6:7], v[8:9], v[6:7]
	v_bfe_u32 v14, v4, 16, 1
	v_bfe_u32 v15, v5, 16, 1
	v_bfe_u32 v16, v0, 16, 1
	v_bfe_u32 v17, v1, 16, 1
	v_bfe_u32 v8, v7, 16, 1
	v_bfe_u32 v9, v6, 16, 1
	v_bfe_u32 v12, v3, 16, 1
	v_bfe_u32 v13, v2, 16, 1
	v_add3_u32 v1, v1, v17, s63
	v_add3_u32 v0, v0, v16, s63
	v_add3_u32 v5, v5, v15, s63
	v_add3_u32 v4, v4, v14, s63
	v_add3_u32 v13, v2, v13, s63
	v_add3_u32 v12, v3, v12, s63
	v_add3_u32 v2, v6, v9, s63
	v_add3_u32 v3, v7, v8, s63
	v_lshrrev_b32_e32 v4, 16, v4
	v_lshrrev_b32_e32 v5, 16, v5
	v_lshrrev_b32_e32 v0, 16, v0
	v_lshrrev_b32_e32 v1, 16, v1
	v_and_or_b32 v3, v3, s82, v1
	v_and_or_b32 v2, v2, s82, v0
	v_and_or_b32 v1, v12, s82, v5
	v_and_or_b32 v0, v13, s82, v4
	v_lshl_add_u64 v[4:5], v[10:11], 0, v[44:45]
	global_store_dwordx4 v[4:5], v[0:3], off

.LBB0_126:
	v_readlane_b32 s94, v244, 33
	v_readlane_b32 s28, v244, 27
	v_readlane_b32 s96, v244, 32
	v_readlane_b32 s97, v244, 31
	v_readlane_b32 s95, v244, 34
	v_readlane_b32 s29, v244, 28
	v_readlane_b32 s30, v244, 29
	v_readlane_b32 s31, v244, 30
.LBB0_127:
	s_branch .Lskip_rot
.Lrot_entry:
	s_mov_b64 s[12:13], s[94:95]
	v_or_b32_e32 v0, s70, v203
	s_mov_b32 s0, 0x200000
	s_mov_b64 s[12:13], s[94:95]
	v_cmp_gt_i32_e32 vcc, s0, v0
	s_and_saveexec_b64 s[18:19], vcc
	s_cbranch_execz .LBB0_138
	v_and_b32_e32 v1, 31, v209
	v_sub_u32_e32 v1, 0, v1
	s_mov_b32 s0, 0x979a371
	v_cvt_f64_i32_e32 v[2:3], v1
	s_mov_b32 s1, 0x3fda934f
	v_mul_f64 v[2:3], v[2:3], s[0:1]
	v_rndne_f64_e32 v[4:5], v[2:3]
	s_mov_b32 s0, 0x3b39803f
	v_add_f64 v[6:7], v[2:3], -v[4:5]
	s_mov_b32 s1, 0x3c7abc9e
	v_mul_f64 v[8:9], v[6:7], s[0:1]
	s_mov_b32 s0, 0xfefa39ef
	s_mov_b32 s1, 0x3fe62e42
	v_fmac_f64_e32 v[8:9], s[0:1], v[6:7]
	s_mov_b32 s0, 0x6a5dcb37
	v_mov_b32_e32 v6, 0xfca7ab0c
	v_mov_b32_e32 v7, 0x3e928af3
	s_mov_b32 s1, 0x3e5ade15
	v_fmac_f64_e32 v[6:7], s[0:1], v[8:9]
	v_mov_b32_e32 v10, 0x623fde64
	v_mov_b32_e32 v11, 0x3ec71dee
	v_fmac_f64_e32 v[10:11], v[8:9], v[6:7]
	v_mov_b32_e32 v6, 0x7c89e6b0
	v_mov_b32_e32 v7, 0x3efa0199
	v_fmac_f64_e32 v[6:7], v[8:9], v[10:11]
	v_mov_b32_e32 v10, 0x14761f6e
	v_mov_b32_e32 v11, 0x3f2a01a0
	v_fmac_f64_e32 v[10:11], v[8:9], v[6:7]
	v_mov_b32_e32 v6, 0x1852b7b0
	v_mov_b32_e32 v7, 0x3f56c16c
	v_fmac_f64_e32 v[6:7], v[8:9], v[10:11]
	v_mov_b32_e32 v10, 0x11122322
	v_mov_b32_e32 v11, 0x3f811111
	v_fmac_f64_e32 v[10:11], v[8:9], v[6:7]
	v_mov_b32_e32 v6, 0x555502a1
	v_mov_b32_e32 v7, 0x3fa55555
	v_fmac_f64_e32 v[6:7], v[8:9], v[10:11]
	v_mov_b32_e32 v10, 0x55555511
	v_mov_b32_e32 v11, 0x3fc55555
	v_fmac_f64_e32 v[10:11], v[8:9], v[6:7]
	v_mov_b32_e32 v6, 11
	v_mov_b32_e32 v7, 0x3fe00000
	s_mov_b32 s0, 0
	v_fmac_f64_e32 v[6:7], v[8:9], v[10:11]
	s_mov_b32 s1, 0x40900000
	v_fma_f64 v[6:7], v[8:9], v[6:7], 1.0
	v_cmp_nlt_f64_e32 vcc, s[0:1], v[2:3]
	s_mov_b32 s0, 0
	v_fma_f64 v[6:7], v[8:9], v[6:7], 1.0
	v_cvt_i32_f64_e32 v1, v[4:5]
	s_mov_b32 s1, 0xc090cc00
	v_ldexp_f64 v[4:5], v[6:7], v1
	v_mov_b32_e32 v1, 0x7ff00000
	v_cmp_ngt_f64_e64 s[0:1], s[0:1], v[2:3]
	v_cndmask_b32_e32 v1, v1, v5, vcc
	s_and_b64 vcc, s[0:1], vcc
	s_lshl_b32 s22, s30, 8
	v_cndmask_b32_e64 v3, 0, v1, s[0:1]
	v_cndmask_b32_e32 v2, 0, v4, vcc
	v_ashrrev_i32_e32 v1, 31, v0
	v_cvt_f32_f64_e32 v6, v[2:3]
	v_lshl_add_u64 v[2:3], v[0:1], 2, s[58:59]
	s_mov_b64 s[0:1], 0x3a800000
	s_ashr_i32 s23, s22, 31
	s_mov_b32 s26, 0x6dc9c883
	s_mov_b32 s36, 0x54442d18
	v_lshl_add_u64 v[2:3], v[2:3], 0, s[0:1]
	s_lshl_b64 s[10:11], s[22:23], 2
	s_mov_b64 s[24:25], 0
	s_mov_b32 s27, 0x3fc45f30
	s_mov_b32 s37, 0x401921fb
	s_brev_b32 s23, 18
	s_mov_b32 s34, 0xfe5163ab
	v_mov_b32_e32 v5, 0
	s_mov_b32 s35, 0x3c439041
	s_mov_b32 s40, 0xdb629599
	s_mov_b32 s41, 0xf534ddc0
	s_mov_b32 s42, 0xfc2757d1
	s_mov_b32 s43, 0x4e441529
	s_mov_b32 s44, 0xa2f9836e
	s_mov_b32 s45, 0x3fc90fda
	s_mov_b32 s46, 0x3f22f983
	s_mov_b32 s47, 0xbfc90fda
	v_mov_b32_e32 v1, 0x3c0881c4
	v_mov_b32_e32 v7, 0xbab64f3b
	s_brev_b32 s48, 1
	s_movk_i32 s49, 0x1f8
	s_mov_b32 s50, 0x1fffff
	v_not_b32_e32 v8, 63
	v_not_b32_e32 v9, 31
	v_mov_b32_e32 v10, 0x7fc00000
	s_branch .LBB0_130

.LBB0_138:
	s_or_b64 exec, exec, s[18:19]
	s_mov_b64 s[4:5], 0
	s_mov_b64 s[94:95], s[12:13]
	v_readlane_b32 s0, v244, 62
	v_readlane_b32 s1, v244, 63
	s_nop 4
	s_branch .Leven_items
.Lskip_rot:
	s_mov_b64 s[4:5], 0
.LBB0_139:
	s_and_b64 vcc, exec, s[4:5]
	s_cbranch_vccz .LBB0_147
